# v5 + deferred table conversion loop software-pipelined: two chunk pairs (16 loads) in flight per iteration
# baseline (speedup 1.0000x reference)
; DEVI void convert_chunk_fp8(const float* __restrict__ src, unsigned char* __restrict__ dst, float scale, int tid) {
;   int o = tid * 16;
;   uint4 r;
;   unsigned rr[4];
; #pragma unroll
;   for (int q = 0; q < 4; ++q) {
;     float4 a = *reinterpret_cast<const float4*>(src + o + q * 4);
;     int p = __builtin_amdgcn_cvt_pk_fp8_f32(a.x * scale, a.y * scale, 0, false);
;     p = __builtin_amdgcn_cvt_pk_fp8_f32(a.z * scale, a.w * scale, p, true);
;     rr[q] = (unsigned)p;
;   }
;   r = make_uint4(rr[0], rr[1], rr[2], rr[3]);
;   *reinterpret_cast<uint4*>(dst + o) = r;
; }
; DEVI void phase_prep(const Params& P, int l, char* smem) {
;     ...
;     } else if (id < C1) {
;       int q = id - C0;
;       convert_chunk_fp8(P.in[26] + (long)l * 16777216 + (long)q * 4096, (unsigned char*)(ws + O_UTB) + (long)q * 4096, U_SCALE, tid);
;     } else if (id < C2) {
;       int q = id - C1;
;       convert_chunk_fp8(P.in[27] + (long)l * 16777216 + (long)q * 4096, (unsigned char*)(ws + O_VTB) + (long)q * 4096, V_SCALE, tid);
.Ltb_loop_a:
	s_add_i32 s61, s60, 0x0
	s_lshl_b32 s61, s61, 14
	s_add_u32 s42, s54, s61
	s_addc_u32 s43, s55, 0
	s_add_u32 s44, s56, s61
	s_addc_u32 s45, s57, 0
	global_load_dwordx4 v[208:211], v248, s[42:43]
	global_load_dwordx4 v[212:215], v248, s[42:43] offset:16
	global_load_dwordx4 v[216:219], v248, s[42:43] offset:32
	global_load_dwordx4 v[220:223], v248, s[42:43] offset:48
	global_load_dwordx4 v[224:227], v248, s[44:45]
	global_load_dwordx4 v[228:231], v248, s[44:45] offset:16
	global_load_dwordx4 v[232:235], v248, s[44:45] offset:32
	global_load_dwordx4 v[236:239], v248, s[44:45] offset:48
	s_add_i32 s61, s60, 0x200
	s_lshl_b32 s61, s61, 14
	s_add_u32 s42, s54, s61
	s_addc_u32 s43, s55, 0
	s_add_u32 s44, s56, s61
	s_addc_u32 s45, s57, 0
	global_load_dwordx4 v[100:103], v248, s[42:43]
	global_load_dwordx4 v[104:107], v248, s[42:43] offset:16
	global_load_dwordx4 v[108:111], v248, s[42:43] offset:32
	global_load_dwordx4 v[112:115], v248, s[42:43] offset:48
	global_load_dwordx4 v[116:119], v248, s[44:45]
	global_load_dwordx4 v[120:123], v248, s[44:45] offset:16
	global_load_dwordx4 v[124:127], v248, s[44:45] offset:32
	global_load_dwordx4 v[128:131], v248, s[44:45] offset:48
	s_add_i32 s61, s60, 0x0
	s_lshl_b32 s61, s61, 12
	s_add_u32 s58, s61, 0x2500000
	s_mov_b32 s59, 0
	v_lshl_add_u64 v[202:203], v[250:251], 0, s[58:59]
	s_add_u32 s58, s61, 0x4500000
	v_lshl_add_u64 v[204:205], v[250:251], 0, s[58:59]
	s_waitcnt vmcnt(12)
	v_mul_f32_e32 v208, 0x42800000, v208
	v_mul_f32_e32 v209, 0x42800000, v209
	v_mul_f32_e32 v210, 0x42800000, v210
	v_mul_f32_e32 v211, 0x42800000, v211
	v_mul_f32_e32 v212, 0x42800000, v212
	v_mul_f32_e32 v213, 0x42800000, v213
	v_mul_f32_e32 v214, 0x42800000, v214
	v_mul_f32_e32 v215, 0x42800000, v215
	v_mul_f32_e32 v216, 0x42800000, v216
	v_mul_f32_e32 v217, 0x42800000, v217
	v_mul_f32_e32 v218, 0x42800000, v218
	v_mul_f32_e32 v219, 0x42800000, v219
	v_mul_f32_e32 v220, 0x42800000, v220
	v_mul_f32_e32 v221, 0x42800000, v221
	v_mul_f32_e32 v222, 0x42800000, v222
	v_mul_f32_e32 v223, 0x42800000, v223
	v_mov_b32_e32 v240, v89
	v_mov_b32_e32 v241, v89
	v_mov_b32_e32 v242, v89
	v_mov_b32_e32 v243, v89
	v_cvt_pk_fp8_f32 v240, v208, v209
	v_cvt_pk_fp8_f32 v241, v212, v213
	v_cvt_pk_fp8_f32 v242, v216, v217
	v_cvt_pk_fp8_f32 v243, v220, v221
	v_cvt_pk_fp8_f32 v240, v210, v211 op_sel:[0,0,1]
	v_cvt_pk_fp8_f32 v241, v214, v215 op_sel:[0,0,1]
	v_cvt_pk_fp8_f32 v242, v218, v219 op_sel:[0,0,1]
	v_cvt_pk_fp8_f32 v243, v222, v223 op_sel:[0,0,1]
	global_store_dwordx4 v[202:203], v[240:243], off
	s_waitcnt vmcnt(9)
	v_mul_f32_e32 v224, 0x41000000, v224
	v_mul_f32_e32 v225, 0x41000000, v225
	v_mul_f32_e32 v226, 0x41000000, v226
	v_mul_f32_e32 v227, 0x41000000, v227
	v_mul_f32_e32 v228, 0x41000000, v228
	v_mul_f32_e32 v229, 0x41000000, v229
	v_mul_f32_e32 v230, 0x41000000, v230
	v_mul_f32_e32 v231, 0x41000000, v231
	v_mul_f32_e32 v232, 0x41000000, v232
	v_mul_f32_e32 v233, 0x41000000, v233
	v_mul_f32_e32 v234, 0x41000000, v234
	v_mul_f32_e32 v235, 0x41000000, v235
	v_mul_f32_e32 v236, 0x41000000, v236
	v_mul_f32_e32 v237, 0x41000000, v237
	v_mul_f32_e32 v238, 0x41000000, v238
	v_mul_f32_e32 v239, 0x41000000, v239
	v_mov_b32_e32 v244, v89
	v_mov_b32_e32 v245, v89
	v_mov_b32_e32 v246, v89
	v_mov_b32_e32 v247, v89
	v_cvt_pk_fp8_f32 v244, v224, v225
	v_cvt_pk_fp8_f32 v245, v228, v229
	v_cvt_pk_fp8_f32 v246, v232, v233
	v_cvt_pk_fp8_f32 v247, v236, v237
	v_cvt_pk_fp8_f32 v244, v226, v227 op_sel:[0,0,1]
	v_cvt_pk_fp8_f32 v245, v230, v231 op_sel:[0,0,1]
	v_cvt_pk_fp8_f32 v246, v234, v235 op_sel:[0,0,1]
	v_cvt_pk_fp8_f32 v247, v238, v239 op_sel:[0,0,1]
	global_store_dwordx4 v[204:205], v[244:247], off
	s_add_i32 s61, s60, 0x200
	s_lshl_b32 s61, s61, 12
	s_add_u32 s58, s61, 0x2500000
	s_mov_b32 s59, 0
	v_lshl_add_u64 v[202:203], v[250:251], 0, s[58:59]
	s_add_u32 s58, s61, 0x4500000
	v_lshl_add_u64 v[204:205], v[250:251], 0, s[58:59]
	s_waitcnt vmcnt(6)
	v_mul_f32_e32 v100, 0x42800000, v100
	v_mul_f32_e32 v101, 0x42800000, v101
	v_mul_f32_e32 v102, 0x42800000, v102
	v_mul_f32_e32 v103, 0x42800000, v103
	v_mul_f32_e32 v104, 0x42800000, v104
	v_mul_f32_e32 v105, 0x42800000, v105
	v_mul_f32_e32 v106, 0x42800000, v106
	v_mul_f32_e32 v107, 0x42800000, v107
	v_mul_f32_e32 v108, 0x42800000, v108
	v_mul_f32_e32 v109, 0x42800000, v109
	v_mul_f32_e32 v110, 0x42800000, v110
	v_mul_f32_e32 v111, 0x42800000, v111
	v_mul_f32_e32 v112, 0x42800000, v112
	v_mul_f32_e32 v113, 0x42800000, v113
	v_mul_f32_e32 v114, 0x42800000, v114
	v_mul_f32_e32 v115, 0x42800000, v115
	v_mov_b32_e32 v240, v89
	v_mov_b32_e32 v241, v89
	v_mov_b32_e32 v242, v89
	v_mov_b32_e32 v243, v89
	v_cvt_pk_fp8_f32 v240, v100, v101
	v_cvt_pk_fp8_f32 v241, v104, v105
	v_cvt_pk_fp8_f32 v242, v108, v109
	v_cvt_pk_fp8_f32 v243, v112, v113
	v_cvt_pk_fp8_f32 v240, v102, v103 op_sel:[0,0,1]
	v_cvt_pk_fp8_f32 v241, v106, v107 op_sel:[0,0,1]
	v_cvt_pk_fp8_f32 v242, v110, v111 op_sel:[0,0,1]
	v_cvt_pk_fp8_f32 v243, v114, v115 op_sel:[0,0,1]
	global_store_dwordx4 v[202:203], v[240:243], off
	s_waitcnt vmcnt(3)
	v_mul_f32_e32 v116, 0x41000000, v116
	v_mul_f32_e32 v117, 0x41000000, v117
	v_mul_f32_e32 v118, 0x41000000, v118
	v_mul_f32_e32 v119, 0x41000000, v119
	v_mul_f32_e32 v120, 0x41000000, v120
	v_mul_f32_e32 v121, 0x41000000, v121
	v_mul_f32_e32 v122, 0x41000000, v122
	v_mul_f32_e32 v123, 0x41000000, v123
	v_mul_f32_e32 v124, 0x41000000, v124
	v_mul_f32_e32 v125, 0x41000000, v125
	v_mul_f32_e32 v126, 0x41000000, v126
	v_mul_f32_e32 v127, 0x41000000, v127
	v_mul_f32_e32 v128, 0x41000000, v128
	v_mul_f32_e32 v129, 0x41000000, v129
	v_mul_f32_e32 v130, 0x41000000, v130
	v_mul_f32_e32 v131, 0x41000000, v131
	v_mov_b32_e32 v244, v89
	v_mov_b32_e32 v245, v89
	v_mov_b32_e32 v246, v89
	v_mov_b32_e32 v247, v89
	v_cvt_pk_fp8_f32 v244, v116, v117
	v_cvt_pk_fp8_f32 v245, v120, v121
	v_cvt_pk_fp8_f32 v246, v124, v125
	v_cvt_pk_fp8_f32 v247, v128, v129
	v_cvt_pk_fp8_f32 v244, v118, v119 op_sel:[0,0,1]
	v_cvt_pk_fp8_f32 v245, v122, v123 op_sel:[0,0,1]
	v_cvt_pk_fp8_f32 v246, v126, v127 op_sel:[0,0,1]
	v_cvt_pk_fp8_f32 v247, v130, v131 op_sel:[0,0,1]
	global_store_dwordx4 v[204:205], v[244:247], off
	s_addk_i32 s60, 0x400
	s_cmpk_lt_u32 s60, 0x1000
	s_cbranch_scc1 .Ltb_loop_a
	s_cmp_lg_u32 s0, 0
	s_cbranch_scc1 .Ltb_skip_a
	v_readlane_b32 s44, v253, 2
	v_readlane_b32 s45, v253, 3
	v_readlane_b32 s60, v252, 32
	s_nop 4
	s_load_dwordx2 s[42:43], s[44:45], 0x0
	v_lshlrev_b32_e32 v248, 4, v93
	v_lshlrev_b32_e32 v250, 3, v93
	v_mov_b32_e32 v251, 0
	v_lshl_add_u64 v[250:251], v[64:65], 0, v[250:251]
	s_waitcnt lgkmcnt(0)
